# prep section A: the beta sigmoid's 1/x division expansion replaced by v_rcp_f32 like the other sigmoids (shorter dependent chain on wave 0), on top of the combined stack
# speedup vs baseline: 1.0093x; 1.0093x over previous
.LBB0_312:
	s_ashr_i32 s2, s23, 10
	v_and_b32_e32 v134, 63, v135
	s_ashr_i32 s3, s2, 31
	s_bfe_u32 s6, s23, 0x30007
	s_lshl_b64 s[4:5], s[2:3], 13
	s_and_b32 s7, s22, 0x1fc0
	s_andn2_b64 vcc, exec, s[0:1]
	v_cmp_gt_u32_e64 s[0:1], 32, v134
	s_cbranch_vccnz .LBB0_316
	v_or_b32_e32 v1, s7, v134
	v_or_b32_e32 v2, s4, v1
	v_mov_b32_e32 v3, s5
	v_lshlrev_b64 v[2:3], 6, v[2:3]
	v_lshl_add_u64 v[2:3], s[14:15], 0, v[2:3]
	s_lshl_b32 s52, s6, 2
	v_readlane_b32 s2, v251, 53
	v_lshl_add_u64 v[2:3], v[2:3], 0, s[52:53]
	v_mov_b32_e32 v8, s52
	v_readlane_b32 s3, v251, 54
	v_add_u32_e32 v10, -1, v211
	v_add_u32_e32 v11, -2, v211
	v_add_u32_e32 v12, -4, v211
	v_add_u32_e32 v13, -8, v211
	v_readlane_b32 s2, v251, 55
	v_readlane_b32 s3, v251, 56
	s_nop 4
	s_nop 0
	v_and_b32_e32 v2, 64, v211
	v_cmp_lt_i32_e32 vcc, v10, v2
	v_add_u32_e32 v14, -16, v211
	v_subrev_u32_e32 v15, 32, v211
	v_cndmask_b32_e32 v10, v10, v211, vcc
	v_cmp_lt_i32_e32 vcc, v11, v2
	s_mov_b32 s2, 0x3f317217
	v_lshlrev_b32_e32 v10, 2, v10
	v_cndmask_b32_e32 v11, v11, v211, vcc
	v_cmp_lt_i32_e32 vcc, v12, v2
	v_lshlrev_b32_e32 v11, 2, v11
	v_lshl_add_u32 v16, v134, 2, 0
	v_cndmask_b32_e32 v12, v12, v211, vcc
	v_cmp_lt_i32_e32 vcc, v13, v2
	v_lshlrev_b32_e32 v12, 2, v12
	v_add_u32_e32 v17, 0x20500, v16
	v_cndmask_b32_e32 v13, v13, v211, vcc
	v_cmp_lt_i32_e32 vcc, v14, v2
	v_lshlrev_b32_e32 v13, 2, v13
	v_add_u32_e32 v16, 0x20600, v16
	v_cndmask_b32_e32 v14, v14, v211, vcc
	v_cmp_lt_i32_e32 vcc, v15, v2
	s_waitcnt vmcnt(8)
	v_mov_b32_e32 v1, v242
	v_mov_b32_e32 v9, v244
	v_mov_b32_e32 v8, v245
	v_mov_b32_e32 v3, v243
	v_add_f32_e32 v1, v1, v9
	v_mul_f32_e32 v9, 0x3fb8aa3b, v1
	v_exp_f32_e32 v9, v9
	v_cndmask_b32_e32 v15, v15, v211, vcc
	v_mul_f32_e32 v8, 0x3fb8aa3b, v8
	v_exp_f32_e32 v8, v8
	v_add_f32_e32 v9, 1.0, v9
	v_cmp_gt_f32_e32 vcc, s51, v9
	v_mul_f32_e32 v3, 0xbfb8aa3b, v3
	v_exp_f32_e32 v3, v3
	v_cndmask_b32_e64 v18, 0, 32, vcc
	v_ldexp_f32 v9, v9, v18
	v_log_f32_e32 v9, v9
	v_cndmask_b32_e32 v18, 0, v213, vcc
	v_add_f32_e32 v3, 1.0, v3
	v_mul_f32_e32 v19, 0x3f317217, v9
	v_fma_f32 v19, v9, s2, -v19
	v_fmac_f32_e32 v19, 0x3377d1cf, v9
	s_mov_b32 s2, 0x7f800000
	v_fmac_f32_e32 v19, 0x3f317217, v9
	v_cmp_lt_f32_e64 vcc, |v9|, s2
	s_mov_b32 s2, 0x41a00000
	s_nop 0
	v_cndmask_b32_e32 v9, v9, v19, vcc
	v_sub_f32_e32 v9, v9, v18
	v_cmp_lt_f32_e32 vcc, s2, v1
	s_nop 1
	v_cndmask_b32_e32 v1, v9, v1, vcc
	v_mul_f32_e64 v9, v1, -v8
	ds_bpermute_b32 v10, v10, v9
	v_cmp_eq_u32_e32 vcc, 0, v134
	s_waitcnt lgkmcnt(0)
	v_fma_f32 v1, v1, -v8, v10
	v_cndmask_b32_e32 v1, v1, v9, vcc
	ds_bpermute_b32 v8, v11, v1
	v_cmp_gt_u32_e32 vcc, 2, v134
	s_nop 0
	v_cmp_gt_u32_e64 s[2:3], 8, v134
	s_waitcnt lgkmcnt(0)
	v_add_f32_e32 v8, v1, v8
	v_cndmask_b32_e32 v1, v8, v1, vcc
	ds_bpermute_b32 v8, v12, v1
	v_cmp_gt_u32_e32 vcc, 4, v134
	v_lshlrev_b32_e32 v9, 2, v14
	s_nop 0
	v_lshlrev_b32_e32 v10, 2, v15
	s_waitcnt lgkmcnt(0)
	v_add_f32_e32 v8, v1, v8
	v_cndmask_b32_e32 v1, v8, v1, vcc
	ds_bpermute_b32 v8, v13, v1
	s_nop 0
	s_nop 0
	s_nop 0
	s_waitcnt lgkmcnt(0)
	v_add_f32_e32 v8, v1, v8
	v_cndmask_b32_e64 v1, v8, v1, s[2:3]
	ds_bpermute_b32 v8, v9, v1
	v_cmp_gt_u32_e64 s[2:3], 16, v134
	s_nop 0
	s_nop 0
	s_nop 0
	s_waitcnt lgkmcnt(0)
	v_add_f32_e32 v8, v1, v8
	v_cndmask_b32_e64 v8, v8, v1, s[2:3]
	ds_bpermute_b32 v1, v10, v8
	s_nop 0
	s_nop 0
	v_rcp_f32_e32 v3, v3
	s_nop 0
	ds_write_b32 v16, v3
	s_waitcnt lgkmcnt(1)
	v_add_f32_e32 v1, v8, v1
	v_cndmask_b32_e64 v3, v1, v8, s[0:1]
	v_cmp_eq_u32_e32 vcc, 63, v134
	ds_write_b32 v17, v3
	s_and_saveexec_b64 s[0:1], vcc
	s_cbranch_execz .LBB0_315
	v_mul_f32_e32 v1, 0x3fb8aa3b, v1
	v_exp_f32_e32 v1, v1
	s_add_u32 s2, s10, s20
	s_addc_u32 s3, s11, s21
	global_store_dword v0, v1, s[2:3]
